# on top of flat release poll: forgetting-attention step loop head reads one flag word per lane early and issues the next K/V DMA before testing the exhausted flags (shorter serial chain after the step
# speedup vs baseline: 1.0039x; 1.0039x over previous
.LBB0_878:
	s_waitcnt vmcnt(0) lgkmcnt(0)
	s_barrier
	s_cmp_eq_u32 s33, 0
	s_cselect_b64 s[2:3], -1, 0
	s_cmp_lg_u32 s33, 0
	s_cselect_b64 s[0:1], -1, 0
	s_andn2_b32 s4, 8, s55
	s_lshl_b32 s4, s4, 2
	s_add_i32 s4, s4, 0x20800
	v_mbcnt_lo_u32_b32 v247, -1, 0
	v_and_b32_e32 v247, 7, v247
	v_lshl_add_u32 v247, v247, 2, s4
	ds_read_b32 v246, v247
	s_add_i32 s4, s56, 2
	s_cmp_ge_u32 s4, s52
	s_cbranch_scc1 .Lfx_nodma
	v_readlane_b32 s8, v254, 38
	v_readlane_b32 s9, v254, 39
	s_mov_b32 s10, 0xfff60000
	s_mov_b32 s12, 0xfff40000
	v_lshl_add_u64 v[66:67], v[182:183], 0, s[8:9]
	s_mov_b32 s11, -1
	s_mov_b32 s13, -1
	v_lshl_add_u64 v[68:69], v[66:67], 0, s[10:11]
	s_add_i32 s4, s54, s59
	s_mov_b32 s5, m0
	s_mov_b32 m0, s4
	s_nop 0
	global_load_lds_dwordx4 v[68:69], off
	s_mov_b32 m0, s5
	v_lshl_add_u64 v[66:67], v[66:67], 0, s[12:13]
	s_add_i32 s5, s4, 0x2000
	s_mov_b32 s7, m0
	s_mov_b32 m0, s5
	s_nop 0
	global_load_lds_dwordx4 v[66:67], off
	s_mov_b32 m0, s7
	v_lshl_add_u64 v[66:67], v[184:185], 0, s[8:9]
	v_lshl_add_u64 v[68:69], v[66:67], 0, s[10:11]
	s_add_i32 s5, s4, 0x4000
	s_mov_b32 s7, m0
	s_mov_b32 m0, s5
	s_nop 0
	global_load_lds_dwordx4 v[68:69], off
	s_mov_b32 m0, s7
	v_lshl_add_u64 v[66:67], v[66:67], 0, s[12:13]
	s_addk_i32 s4, 0x6000
	s_mov_b32 s5, m0
	s_mov_b32 m0, s4
	s_nop 0
	global_load_lds_dwordx4 v[66:67], off
	s_mov_b32 m0, s5
.Lfx_nodma:
	s_waitcnt lgkmcnt(0)
	v_cmp_eq_u32_e64 s[4:5], 0, v246
	s_cmp_lg_u64 s[4:5], 0
	s_cselect_b64 s[4:5], -1, 0
	s_or_b64 s[4:5], s[4:5], s[2:3]
	s_andn2_b64 vcc, exec, s[4:5]
	s_cbranch_vccnz .LBB0_896
